# grid barrier: L1 invalidate issued at arrival (members before first poll, XCD leader together with the L2 write-back) instead of after the release
# speedup vs baseline: 1.0041x; 1.0041x over previous
.LBB0_115:
	s_or_b64 exec, exec, s[12:13]
	v_cvt_f32_u32_e32 v4, v2
	s_waitcnt vmcnt(0)
	v_readfirstlane_b32 s6, v3
	v_sub_u32_e32 v3, 0, v2
	v_rcp_iflag_f32_e32 v4, v4
	v_add_u32_e32 v5, s6, v1
	v_mul_f32_e32 v4, 0x4f7ffffe, v4
	v_cvt_u32_f32_e32 v4, v4
	v_mul_lo_u32 v1, v3, v4
	v_mul_hi_u32 v1, v4, v1
	v_add_u32_e32 v1, v4, v1
	v_mul_hi_u32 v1, v5, v1
	v_mul_lo_u32 v3, v1, v2
	v_sub_u32_e32 v3, v5, v3
	v_add_u32_e32 v4, 1, v1
	v_sub_u32_e32 v6, v3, v2
	v_cmp_ge_u32_e32 vcc, v3, v2
	s_nop 1
	v_cndmask_b32_e32 v1, v1, v4, vcc
	v_cndmask_b32_e32 v3, v3, v6, vcc
	v_add_u32_e32 v4, 1, v1
	v_cmp_ge_u32_e32 vcc, v3, v2
	v_add_u32_e32 v3, 1, v5
	s_nop 0
	v_cndmask_b32_e32 v1, v1, v4, vcc
	v_mul_lo_u32 v4, v2, v1
	v_add_u32_e32 v2, v4, v2
	v_cmp_ne_u32_e32 vcc, v3, v2
	s_and_saveexec_b64 s[6:7], vcc
	s_xor_b64 s[12:13], exec, s[6:7]
	s_cbranch_execz .LBB0_129
	v_readlane_b32 s6, v253, 18
	v_readlane_b32 s7, v253, 19
	s_waitcnt lgkmcnt(0)
	s_nop 3
	buffer_inv sc1
	global_load_dword v0, v64, s[6:7] sc1
	s_waitcnt vmcnt(0)
	v_cmp_eq_u32_e32 vcc, v0, v1
	s_and_saveexec_b64 s[16:17], vcc
	s_cbranch_execz .LBB0_128
	s_mov_b32 s6, 1
	s_mov_b64 s[20:21], 0
	s_branch .LBB0_119

.LBB0_128:
	s_or_b64 exec, exec, s[16:17]
	s_waitcnt vmcnt(0)

	s_waitcnt vmcnt(0)
.LBB0_129:
	s_andn2_saveexec_b64 s[6:7], s[12:13]
	s_cbranch_execz .LBB0_149
	s_mov_b64 s[12:13], exec
	buffer_wbl2 sc1
	buffer_inv sc1
	s_waitcnt lgkmcnt(0)
	s_waitcnt vmcnt(0)
	v_mbcnt_lo_u32_b32 v1, s12, 0
	v_mbcnt_hi_u32_b32 v1, s13, v1
	v_cmp_eq_u32_e32 vcc, 0, v1
	s_and_saveexec_b64 s[16:17], vcc
	s_cbranch_execz .LBB0_132
	s_bcnt1_i32_b64 s6, s[12:13]
	v_mov_b32_e32 v2, s6
	v_readlane_b32 s6, v253, 20
	v_readlane_b32 s7, v253, 21
	s_nop 4
	global_atomic_add v2, v64, v2, s[6:7] sc0

.LBB0_146:
	s_or_b64 exec, exec, s[12:13]
	s_mov_b64 s[12:13], exec
	v_mbcnt_lo_u32_b32 v0, s12, 0
	v_mbcnt_hi_u32_b32 v0, s13, v0
	v_cmp_eq_u32_e32 vcc, 0, v0
	s_waitcnt vmcnt(0)

	s_and_saveexec_b64 s[16:17], vcc
	s_cbranch_execz .LBB0_148
	s_bcnt1_i32_b64 s6, s[12:13]
	v_mov_b32_e32 v0, s6
	v_readlane_b32 s6, v253, 18
	v_readlane_b32 s7, v253, 19
	s_nop 4
	global_atomic_add v64, v0, s[6:7]

.LBB0_1155:
	s_or_b64 exec, exec, s[12:13]
	v_cvt_f32_u32_e32 v4, v2
	s_waitcnt vmcnt(0)
	v_readfirstlane_b32 s6, v3
	v_sub_u32_e32 v3, 0, v2
	v_rcp_iflag_f32_e32 v4, v4
	v_add_u32_e32 v5, s6, v1
	v_mul_f32_e32 v4, 0x4f7ffffe, v4
	v_cvt_u32_f32_e32 v4, v4
	v_mul_lo_u32 v1, v3, v4
	v_mul_hi_u32 v1, v4, v1
	v_add_u32_e32 v1, v4, v1
	v_mul_hi_u32 v1, v5, v1
	v_mul_lo_u32 v3, v1, v2
	v_sub_u32_e32 v3, v5, v3
	v_add_u32_e32 v4, 1, v1
	v_cmp_ge_u32_e32 vcc, v3, v2
	s_nop 1
	v_cndmask_b32_e32 v1, v1, v4, vcc
	v_sub_u32_e32 v4, v3, v2
	v_cndmask_b32_e32 v3, v3, v4, vcc
	v_add_u32_e32 v4, 1, v1
	v_cmp_ge_u32_e32 vcc, v3, v2
	v_add_u32_e32 v3, 1, v5
	s_nop 0
	v_cndmask_b32_e32 v1, v1, v4, vcc
	v_mul_lo_u32 v4, v2, v1
	v_add_u32_e32 v2, v4, v2
	v_cmp_ne_u32_e32 vcc, v3, v2
	s_and_saveexec_b64 s[6:7], vcc
	s_xor_b64 s[12:13], exec, s[6:7]
	s_cbranch_execz .LBB0_1169
	v_readlane_b32 s6, v253, 18
	v_readlane_b32 s7, v253, 19
	s_waitcnt lgkmcnt(0)
	s_nop 3
	buffer_inv sc1
	global_load_dword v0, v64, s[6:7] sc1
	s_waitcnt vmcnt(0)
	v_cmp_eq_u32_e32 vcc, v0, v1
	s_and_saveexec_b64 s[16:17], vcc
	s_cbranch_execz .LBB0_1168
	s_mov_b32 s6, 1
	s_mov_b64 s[20:21], 0
	s_branch .LBB0_1159

.LBB0_1797:
	s_or_b64 exec, exec, s[12:13]
	v_cvt_f32_u32_e32 v4, v2
	s_waitcnt vmcnt(0)
	v_readfirstlane_b32 s2, v3
	v_sub_u32_e32 v3, 0, v2
	v_rcp_iflag_f32_e32 v4, v4
	v_add_u32_e32 v5, s2, v1
	v_mul_f32_e32 v4, 0x4f7ffffe, v4
	v_cvt_u32_f32_e32 v4, v4
	v_mul_lo_u32 v1, v3, v4
	v_mul_hi_u32 v1, v4, v1
	v_add_u32_e32 v1, v4, v1
	v_mul_hi_u32 v1, v5, v1
	v_mul_lo_u32 v3, v1, v2
	v_sub_u32_e32 v3, v5, v3
	v_add_u32_e32 v4, 1, v1
	v_cmp_ge_u32_e32 vcc, v3, v2
	s_nop 1
	v_cndmask_b32_e32 v1, v1, v4, vcc
	v_sub_u32_e32 v4, v3, v2
	v_cndmask_b32_e32 v3, v3, v4, vcc
	v_add_u32_e32 v4, 1, v1
	v_cmp_ge_u32_e32 vcc, v3, v2
	v_add_u32_e32 v3, 1, v5
	s_nop 0
	v_cndmask_b32_e32 v1, v1, v4, vcc
	v_mul_lo_u32 v4, v2, v1
	v_add_u32_e32 v2, v4, v2
	v_cmp_ne_u32_e32 vcc, v3, v2
	s_and_saveexec_b64 s[2:3], vcc
	s_xor_b64 s[12:13], exec, s[2:3]
	s_cbranch_execz .LBB0_1811
	v_readlane_b32 s2, v253, 18
	v_readlane_b32 s3, v253, 19
	s_waitcnt lgkmcnt(0)
	s_nop 3
	buffer_inv sc1
	global_load_dword v0, v64, s[2:3] sc1
	s_waitcnt vmcnt(0)
	v_cmp_eq_u32_e32 vcc, v0, v1
	s_and_saveexec_b64 s[20:21], vcc
	s_cbranch_execz .LBB0_1810
	s_mov_b32 s2, 1
	s_mov_b64 s[28:29], 0
	s_branch .LBB0_1801

.LBB0_1810:
	s_or_b64 exec, exec, s[20:21]
	s_waitcnt vmcnt(0)

	s_waitcnt vmcnt(0)
.LBB0_1811:
	s_andn2_saveexec_b64 s[2:3], s[12:13]
	s_cbranch_execz .LBB0_1831
	s_mov_b64 s[12:13], exec
	buffer_wbl2 sc1
	buffer_inv sc1
	s_waitcnt lgkmcnt(0)
	s_waitcnt vmcnt(0)
	v_mbcnt_lo_u32_b32 v1, s12, 0
	v_mbcnt_hi_u32_b32 v1, s13, v1
	v_cmp_eq_u32_e32 vcc, 0, v1
	s_and_saveexec_b64 s[20:21], vcc
	s_cbranch_execz .LBB0_1814
	s_bcnt1_i32_b64 s2, s[12:13]
	v_mov_b32_e32 v2, s2
	v_readlane_b32 s2, v253, 20
	v_readlane_b32 s3, v253, 21
	s_nop 4
	global_atomic_add v2, v64, v2, s[2:3] sc0

.LBB0_1828:
	s_or_b64 exec, exec, s[12:13]
	s_mov_b64 s[12:13], exec
	v_mbcnt_lo_u32_b32 v0, s12, 0
	v_mbcnt_hi_u32_b32 v0, s13, v0
	v_cmp_eq_u32_e32 vcc, 0, v0
	s_waitcnt vmcnt(0)

	s_and_saveexec_b64 s[20:21], vcc
	s_cbranch_execz .LBB0_1830
	s_bcnt1_i32_b64 s2, s[12:13]
	v_mov_b32_e32 v0, s2
	v_readlane_b32 s2, v253, 18
	v_readlane_b32 s3, v253, 19
	s_nop 4
	global_atomic_add v64, v0, s[2:3]

.LBB0_1924:
	s_or_b64 exec, exec, s[12:13]
	v_cvt_f32_u32_e32 v4, v2
	s_waitcnt vmcnt(0)
	v_readfirstlane_b32 s2, v3
	v_sub_u32_e32 v3, 0, v2
	v_rcp_iflag_f32_e32 v4, v4
	v_add_u32_e32 v5, s2, v1
	v_mul_f32_e32 v4, 0x4f7ffffe, v4
	v_cvt_u32_f32_e32 v4, v4
	v_mul_lo_u32 v1, v3, v4
	v_mul_hi_u32 v1, v4, v1
	v_add_u32_e32 v1, v4, v1
	v_mul_hi_u32 v1, v5, v1
	v_mul_lo_u32 v3, v1, v2
	v_sub_u32_e32 v3, v5, v3
	v_add_u32_e32 v4, 1, v1
	v_cmp_ge_u32_e32 vcc, v3, v2
	s_nop 1
	v_cndmask_b32_e32 v1, v1, v4, vcc
	v_sub_u32_e32 v4, v3, v2
	v_cndmask_b32_e32 v3, v3, v4, vcc
	v_add_u32_e32 v4, 1, v1
	v_cmp_ge_u32_e32 vcc, v3, v2
	v_add_u32_e32 v3, 1, v5
	s_nop 0
	v_cndmask_b32_e32 v1, v1, v4, vcc
	v_mul_lo_u32 v4, v2, v1
	v_add_u32_e32 v2, v4, v2
	v_cmp_ne_u32_e32 vcc, v3, v2
	s_and_saveexec_b64 s[2:3], vcc
	s_xor_b64 s[12:13], exec, s[2:3]
	s_cbranch_execz .LBB0_1938
	v_readlane_b32 s2, v253, 18
	v_readlane_b32 s3, v253, 19
	s_waitcnt lgkmcnt(0)
	s_nop 3
	buffer_inv sc1
	global_load_dword v0, v64, s[2:3] sc1
	s_waitcnt vmcnt(0)
	v_cmp_eq_u32_e32 vcc, v0, v1
	s_and_saveexec_b64 s[20:21], vcc
	s_cbranch_execz .LBB0_1937
	s_mov_b32 s2, 1
	s_mov_b64 s[42:43], 0
	s_branch .LBB0_1928

.LBB0_2187:
	s_or_b64 exec, exec, s[12:13]
	v_cvt_f32_u32_e32 v4, v2
	s_waitcnt vmcnt(0)
	v_readfirstlane_b32 s2, v3
	v_sub_u32_e32 v3, 0, v2
	v_rcp_iflag_f32_e32 v4, v4
	v_add_u32_e32 v5, s2, v1
	v_mul_f32_e32 v4, 0x4f7ffffe, v4
	v_cvt_u32_f32_e32 v4, v4
	v_mul_lo_u32 v1, v3, v4
	v_mul_hi_u32 v1, v4, v1
	v_add_u32_e32 v1, v4, v1
	v_mul_hi_u32 v1, v5, v1
	v_mul_lo_u32 v3, v1, v2
	v_sub_u32_e32 v3, v5, v3
	v_add_u32_e32 v4, 1, v1
	v_cmp_ge_u32_e32 vcc, v3, v2
	s_nop 1
	v_cndmask_b32_e32 v1, v1, v4, vcc
	v_sub_u32_e32 v4, v3, v2
	v_cndmask_b32_e32 v3, v3, v4, vcc
	v_add_u32_e32 v4, 1, v1
	v_cmp_ge_u32_e32 vcc, v3, v2
	v_add_u32_e32 v3, 1, v5
	s_nop 0
	v_cndmask_b32_e32 v1, v1, v4, vcc
	v_mul_lo_u32 v4, v2, v1
	v_add_u32_e32 v2, v4, v2
	v_cmp_ne_u32_e32 vcc, v3, v2
	s_and_saveexec_b64 s[2:3], vcc
	s_xor_b64 s[12:13], exec, s[2:3]
	s_cbranch_execz .LBB0_2201
	v_readlane_b32 s2, v253, 18
	v_readlane_b32 s3, v253, 19
	s_waitcnt lgkmcnt(0)
	s_nop 3
	buffer_inv sc1
	global_load_dword v0, v64, s[2:3] sc1
	s_waitcnt vmcnt(0)
	v_cmp_eq_u32_e32 vcc, v0, v1
	s_and_saveexec_b64 s[16:17], vcc
	s_cbranch_execz .LBB0_2200
	s_mov_b32 s2, 1
	s_mov_b64 s[20:21], 0
	s_branch .LBB0_2191

.LBB0_2201:
	s_andn2_saveexec_b64 s[2:3], s[12:13]
	s_cbranch_execz .LBB0_2221
	s_mov_b64 s[12:13], exec
	buffer_wbl2 sc1
	buffer_inv sc1
	s_waitcnt lgkmcnt(0)
	s_waitcnt vmcnt(0)
	v_mbcnt_lo_u32_b32 v1, s12, 0
	v_mbcnt_hi_u32_b32 v1, s13, v1
	v_cmp_eq_u32_e32 vcc, 0, v1
	s_and_saveexec_b64 s[16:17], vcc
	s_cbranch_execz .LBB0_2204
	s_bcnt1_i32_b64 s2, s[12:13]
	v_mov_b32_e32 v2, s2
	v_readlane_b32 s2, v253, 20
	v_readlane_b32 s3, v253, 21
	s_nop 4
	global_atomic_add v2, v64, v2, s[2:3] sc0

.LBB0_2218:
	s_or_b64 exec, exec, s[12:13]
	s_mov_b64 s[12:13], exec
	v_mbcnt_lo_u32_b32 v0, s12, 0
	v_mbcnt_hi_u32_b32 v0, s13, v0
	v_cmp_eq_u32_e32 vcc, 0, v0
	s_waitcnt vmcnt(0)

	s_and_saveexec_b64 s[16:17], vcc
	s_cbranch_execz .LBB0_2220
	s_bcnt1_i32_b64 s2, s[12:13]
	v_mov_b32_e32 v0, s2
	v_readlane_b32 s2, v253, 18
	v_readlane_b32 s3, v253, 19
	s_nop 4
	global_atomic_add v64, v0, s[2:3]

.LBB0_2261:
	s_or_b64 exec, exec, s[6:7]
	v_cvt_f32_u32_e32 v4, v2
	s_waitcnt vmcnt(0)
	v_readfirstlane_b32 s6, v3
	v_sub_u32_e32 v3, 0, v2
	v_rcp_iflag_f32_e32 v4, v4
	v_add_u32_e32 v5, s6, v1
	v_mul_f32_e32 v4, 0x4f7ffffe, v4
	v_cvt_u32_f32_e32 v4, v4
	v_mul_lo_u32 v1, v3, v4
	v_mul_hi_u32 v1, v4, v1
	v_add_u32_e32 v1, v4, v1
	v_mul_hi_u32 v1, v5, v1
	v_mul_lo_u32 v3, v1, v2
	v_sub_u32_e32 v3, v5, v3
	v_add_u32_e32 v4, 1, v1
	v_cmp_ge_u32_e32 vcc, v3, v2
	s_nop 1
	v_cndmask_b32_e32 v1, v1, v4, vcc
	v_sub_u32_e32 v4, v3, v2
	v_cndmask_b32_e32 v3, v3, v4, vcc
	v_add_u32_e32 v4, 1, v1
	v_cmp_ge_u32_e32 vcc, v3, v2
	v_add_u32_e32 v3, 1, v5
	s_nop 0
	v_cndmask_b32_e32 v1, v1, v4, vcc
	v_mul_lo_u32 v4, v2, v1
	v_add_u32_e32 v2, v4, v2
	v_cmp_ne_u32_e32 vcc, v3, v2
	s_and_saveexec_b64 s[6:7], vcc
	s_xor_b64 s[6:7], exec, s[6:7]
	s_cbranch_execz .LBB0_2275
	v_readlane_b32 s12, v253, 18
	v_readlane_b32 s13, v253, 19
	s_waitcnt lgkmcnt(0)
	s_nop 3
	buffer_inv sc1
	global_load_dword v0, v64, s[12:13] sc1
	s_waitcnt vmcnt(0)
	v_cmp_eq_u32_e32 vcc, v0, v1
	s_and_saveexec_b64 s[12:13], vcc
	s_cbranch_execz .LBB0_2274
	s_mov_b32 s18, 1
	s_mov_b64 s[16:17], 0
	s_branch .LBB0_2265

.LBB0_2274:
	s_or_b64 exec, exec, s[12:13]
	s_waitcnt vmcnt(0)

	s_waitcnt vmcnt(0)

.LBB0_2276:
	s_mov_b64 s[6:7], exec
	buffer_wbl2 sc1
	buffer_inv sc1
	s_waitcnt lgkmcnt(0)
	s_waitcnt vmcnt(0)
	v_mbcnt_lo_u32_b32 v1, s6, 0
	v_mbcnt_hi_u32_b32 v1, s7, v1
	v_cmp_eq_u32_e32 vcc, 0, v1
	s_and_saveexec_b64 s[12:13], vcc
	s_cbranch_execz .LBB0_2278
	s_bcnt1_i32_b64 s6, s[6:7]
	v_mov_b32_e32 v2, s6
	v_readlane_b32 s6, v253, 20
	v_readlane_b32 s7, v253, 21
	s_nop 4
	global_atomic_add v2, v64, v2, s[6:7] sc0

.LBB0_2292:
	s_or_b64 exec, exec, s[6:7]
	s_mov_b64 s[6:7], exec
	v_mbcnt_lo_u32_b32 v0, s6, 0
	v_mbcnt_hi_u32_b32 v0, s7, v0
	v_cmp_eq_u32_e32 vcc, 0, v0
	s_waitcnt vmcnt(0)

	s_and_saveexec_b64 s[12:13], vcc
	s_cbranch_execnz .LBB0_2293
	s_getpc_b64 s[98:99]
